# P1 KW Toeplitz assembly loop hand-rewritten: branch-free, per-lane offsets hoisted, 16 iterations in double-buffered batches of 3 (one load round trip per batch instead of 3 per iteration)
# speedup vs baseline: 1.0040x; 1.0040x over previous
; __device__ __forceinline__ unsigned pk2(float lo, float hi) { const f32x2_h v = {lo, hi}; return __builtin_bit_cast(unsigned, __builtin_convertvector(v, bf16x2_h)); }
; __global__ void __launch_bounds__(512, 2) fwd_megakernel(Params p) {
;     ...
;         for (int i = gt; i < NG * 512 * 64; i += NGT) {
;             const int c8 = i & 1, j = (i >> 1) & 31, c = (i >> 6) & 15, ii = (i >> 10) & 31, g = i >> 15;
;             float v[8];
;             if (j < ii) { const float* s = KT + (((size_t)(g * 2 + 0) * TCH + (ii - j)) * 16 + c) * 16 + 8 * c8;
; #pragma unroll
;                 for (int e = 0; e < 8; ++e) v[e] = s[e]; }
;             else if (j > ii) { const float* s = KT + (((size_t)(g * 2 + 1) * TCH + (j - ii)) * 16 + c) * 16 + 8 * c8;
; #pragma unroll
;                 for (int e = 0; e < 8; ++e) v[e] = s[e]; }
;             else { const float* s0 = KT + (((size_t)(g * 2 + 0) * TCH) * 16 + c) * 16 + 8 * c8; const float* s1 = KT + (((size_t)(g * 2 + 1) * TCH) * 16 + c) * 16 + 8 * c8;
; #pragma unroll
;                 for (int e = 0; e < 8; ++e) v[e] = s0[e] + s1[e] + ((8 * c8 + e) == c ? ssm_d[g * 16 + c] : 0.f); }
;             u32x4 o; o.x = pk2(v[0], v[1]); o.y = pk2(v[2], v[3]); o.z = pk2(v[4], v[5]); o.w = pk2(v[6], v[7]);
;             *(u32x4*)(KW + ((size_t)g * 512 + ii * 16 + c) * 768 + j * 16 + 8 * c8) = o;
;         }
.LBB0_152:
	s_add_u32 s4, s76, 0x500000
	s_addc_u32 s5, s77, 0
	s_add_u32 s6, s76, 0x6100000
	s_addc_u32 s7, s77, 0
	s_mov_b64 s[8:9], s[66:67]
	v_and_b32_e32 v102, 1, v132
	v_bfe_u32 v103, v132, 1, 5
	v_bfe_u32 v104, v132, 6, 4
	v_bfe_u32 v105, v132, 10, 5
	v_lshrrev_b32_e32 v106, 15, v132
	v_sub_u32_e32 v107, v105, v103
	v_sub_u32_e32 v116, 0, v107
	v_max_i32_e32 v109, v107, v116
	v_lshrrev_b32_e32 v108, 31, v107
	v_cmp_eq_u32_e64 s[10:11], 0, v107
	v_lshlrev_b32_e32 v116, 16, v106
	v_lshl_add_u32 v116, v104, 6, v116
	v_lshl_add_u32 v116, v102, 5, v116
	v_add_u32_e32 v111, 0x8000, v116
	v_lshl_add_u32 v110, v108, 15, v116
	v_lshl_add_u32 v110, v109, 10, v110
	v_lshl_add_u32 v112, v106, 4, v104
	v_lshlrev_b32_e32 v112, 2, v112
	v_lshl_add_u32 v117, v105, 4, v104
	v_mul_u32_u24_e32 v117, 0x600, v117
	v_mul_u32_u24_e32 v116, 0xc0000, v106
	v_add_u32_e32 v113, v116, v117
	v_lshl_add_u32 v113, v103, 5, v113
	v_lshl_add_u32 v113, v102, 4, v113
	v_lshlrev_b32_e32 v116, 3, v102
	v_sub_u32_e32 v117, v104, v116
	v_cmp_eq_u32_e32 vcc, 0, v117
	s_nop 1
	v_cndmask_b32_e64 v102, 0, 1.0, vcc
	v_cmp_eq_u32_e32 vcc, 1, v117
	s_nop 1
	v_cndmask_b32_e64 v103, 0, 1.0, vcc
	v_cmp_eq_u32_e32 vcc, 2, v117
	s_nop 1
	v_cndmask_b32_e64 v105, 0, 1.0, vcc
	v_cmp_eq_u32_e32 vcc, 3, v117
	s_nop 1
	v_cndmask_b32_e64 v106, 0, 1.0, vcc
	v_cmp_eq_u32_e32 vcc, 4, v117
	s_nop 1
	v_cndmask_b32_e64 v107, 0, 1.0, vcc
	v_cmp_eq_u32_e32 vcc, 5, v117
	s_nop 1
	v_cndmask_b32_e64 v108, 0, 1.0, vcc
	v_cmp_eq_u32_e32 vcc, 6, v117
	s_nop 1
	v_cndmask_b32_e64 v109, 0, 1.0, vcc
	v_cmp_eq_u32_e32 vcc, 7, v117
	s_nop 1
	v_cndmask_b32_e64 v114, 0, 1.0, vcc
	global_load_dwordx4 v[0:3], v110, s[4:5]
	global_load_dwordx4 v[4:7], v110, s[4:5] offset:16
	global_load_dwordx4 v[8:11], v111, s[4:5]
	global_load_dwordx4 v[12:15], v111, s[4:5] offset:16
	global_load_dword v96, v112, s[8:9]
	s_add_u32 s4, s4, 0x40000
	s_addc_u32 s5, s5, 0
	s_add_u32 s8, s8, 0x100
	s_addc_u32 s9, s9, 0
	global_load_dwordx4 v[16:19], v110, s[4:5]
	global_load_dwordx4 v[20:23], v110, s[4:5] offset:16
	global_load_dwordx4 v[24:27], v111, s[4:5]
	global_load_dwordx4 v[28:31], v111, s[4:5] offset:16
	global_load_dword v97, v112, s[8:9]
	s_add_u32 s4, s4, 0x40000
	s_addc_u32 s5, s5, 0
	s_add_u32 s8, s8, 0x100
	s_addc_u32 s9, s9, 0
	global_load_dwordx4 v[32:35], v110, s[4:5]
	global_load_dwordx4 v[36:39], v110, s[4:5] offset:16
	global_load_dwordx4 v[40:43], v111, s[4:5]
	global_load_dwordx4 v[44:47], v111, s[4:5] offset:16
	global_load_dword v98, v112, s[8:9]
	s_add_u32 s4, s4, 0x40000
	s_addc_u32 s5, s5, 0
	s_add_u32 s8, s8, 0x100
	s_addc_u32 s9, s9, 0
	global_load_dwordx4 v[48:51], v110, s[4:5]
	global_load_dwordx4 v[52:55], v110, s[4:5] offset:16
	global_load_dwordx4 v[56:59], v111, s[4:5]
	global_load_dwordx4 v[60:63], v111, s[4:5] offset:16
	global_load_dword v99, v112, s[8:9]
	s_add_u32 s4, s4, 0x40000
	s_addc_u32 s5, s5, 0
	s_add_u32 s8, s8, 0x100
	s_addc_u32 s9, s9, 0
	global_load_dwordx4 v[64:67], v110, s[4:5]
	global_load_dwordx4 v[68:71], v110, s[4:5] offset:16
	global_load_dwordx4 v[72:75], v111, s[4:5]
	global_load_dwordx4 v[76:79], v111, s[4:5] offset:16
	global_load_dword v100, v112, s[8:9]
	s_add_u32 s4, s4, 0x40000
	s_addc_u32 s5, s5, 0
	s_add_u32 s8, s8, 0x100
	s_addc_u32 s9, s9, 0
	global_load_dwordx4 v[80:83], v110, s[4:5]
	global_load_dwordx4 v[84:87], v110, s[4:5] offset:16
	global_load_dwordx4 v[88:91], v111, s[4:5]
	global_load_dwordx4 v[92:95], v111, s[4:5] offset:16
	global_load_dword v101, v112, s[8:9]
	s_add_u32 s4, s4, 0x40000
	s_addc_u32 s5, s5, 0
	s_add_u32 s8, s8, 0x100
	s_addc_u32 s9, s9, 0
	s_waitcnt vmcnt(15)
	v_add_f32_e32 v8, v0, v8
	v_add_f32_e32 v9, v1, v9
	v_add_f32_e32 v10, v2, v10
	v_add_f32_e32 v11, v3, v11
	v_add_f32_e32 v12, v4, v12
	v_add_f32_e32 v13, v5, v13
	v_add_f32_e32 v14, v6, v14
	v_add_f32_e32 v15, v7, v15
	v_fma_f32 v8, v102, v96, v8
	v_fma_f32 v9, v103, v96, v9
	v_fma_f32 v10, v105, v96, v10
	v_fma_f32 v11, v106, v96, v11
	v_fma_f32 v12, v107, v96, v12
	v_fma_f32 v13, v108, v96, v13
	v_fma_f32 v14, v109, v96, v14
	v_fma_f32 v15, v114, v96, v15
	v_cndmask_b32_e64 v0, v0, v8, s[10:11]
	v_cndmask_b32_e64 v1, v1, v9, s[10:11]
	v_cndmask_b32_e64 v2, v2, v10, s[10:11]
	v_cndmask_b32_e64 v3, v3, v11, s[10:11]
	v_cndmask_b32_e64 v4, v4, v12, s[10:11]
	v_cndmask_b32_e64 v5, v5, v13, s[10:11]
	v_cndmask_b32_e64 v6, v6, v14, s[10:11]
	v_cndmask_b32_e64 v7, v7, v15, s[10:11]
	v_cvt_pk_bf16_f32 v0, v0, v1
	v_cvt_pk_bf16_f32 v1, v2, v3
	v_cvt_pk_bf16_f32 v2, v4, v5
	v_cvt_pk_bf16_f32 v3, v6, v7
	global_store_dwordx4 v113, v[0:3], s[6:7]
	s_add_u32 s6, s6, 0x300000
	s_addc_u32 s7, s7, 0
	v_add_f32_e32 v24, v16, v24
	v_add_f32_e32 v25, v17, v25
	v_add_f32_e32 v26, v18, v26
	v_add_f32_e32 v27, v19, v27
	v_add_f32_e32 v28, v20, v28
	v_add_f32_e32 v29, v21, v29
	v_add_f32_e32 v30, v22, v30
	v_add_f32_e32 v31, v23, v31
	v_fma_f32 v24, v102, v97, v24
	v_fma_f32 v25, v103, v97, v25
	v_fma_f32 v26, v105, v97, v26
	v_fma_f32 v27, v106, v97, v27
	v_fma_f32 v28, v107, v97, v28
	v_fma_f32 v29, v108, v97, v29
	v_fma_f32 v30, v109, v97, v30
	v_fma_f32 v31, v114, v97, v31
	v_cndmask_b32_e64 v16, v16, v24, s[10:11]
	v_cndmask_b32_e64 v17, v17, v25, s[10:11]
	v_cndmask_b32_e64 v18, v18, v26, s[10:11]
	v_cndmask_b32_e64 v19, v19, v27, s[10:11]
	v_cndmask_b32_e64 v20, v20, v28, s[10:11]
	v_cndmask_b32_e64 v21, v21, v29, s[10:11]
	v_cndmask_b32_e64 v22, v22, v30, s[10:11]
	v_cndmask_b32_e64 v23, v23, v31, s[10:11]
	v_cvt_pk_bf16_f32 v16, v16, v17
	v_cvt_pk_bf16_f32 v17, v18, v19
	v_cvt_pk_bf16_f32 v18, v20, v21
	v_cvt_pk_bf16_f32 v19, v22, v23
	global_store_dwordx4 v113, v[16:19], s[6:7]
; __device__ __forceinline__ unsigned pk2(float lo, float hi) { const f32x2_h v = {lo, hi}; return __builtin_bit_cast(unsigned, __builtin_convertvector(v, bf16x2_h)); }
; __global__ void __launch_bounds__(512, 2) fwd_megakernel(Params p) {
;     ...
;         for (int i = gt; i < NG * 512 * 64; i += NGT) {
;             const int c8 = i & 1, j = (i >> 1) & 31, c = (i >> 6) & 15, ii = (i >> 10) & 31, g = i >> 15;
;             float v[8];
;             if (j < ii) { const float* s = KT + (((size_t)(g * 2 + 0) * TCH + (ii - j)) * 16 + c) * 16 + 8 * c8;
; #pragma unroll
;                 for (int e = 0; e < 8; ++e) v[e] = s[e]; }
;             else if (j > ii) { const float* s = KT + (((size_t)(g * 2 + 1) * TCH + (j - ii)) * 16 + c) * 16 + 8 * c8;
; #pragma unroll
;                 for (int e = 0; e < 8; ++e) v[e] = s[e]; }
;             else { const float* s0 = KT + (((size_t)(g * 2 + 0) * TCH) * 16 + c) * 16 + 8 * c8; const float* s1 = KT + (((size_t)(g * 2 + 1) * TCH) * 16 + c) * 16 + 8 * c8;
; #pragma unroll
;                 for (int e = 0; e < 8; ++e) v[e] = s0[e] + s1[e] + ((8 * c8 + e) == c ? ssm_d[g * 16 + c] : 0.f); }
;             u32x4 o; o.x = pk2(v[0], v[1]); o.y = pk2(v[2], v[3]); o.z = pk2(v[4], v[5]); o.w = pk2(v[6], v[7]);
;             *(u32x4*)(KW + ((size_t)g * 512 + ii * 16 + c) * 768 + j * 16 + 8 * c8) = o;
;         }
	s_add_u32 s6, s6, 0x300000
	s_addc_u32 s7, s7, 0
	v_add_f32_e32 v40, v32, v40
	v_add_f32_e32 v41, v33, v41
	v_add_f32_e32 v42, v34, v42
	v_add_f32_e32 v43, v35, v43
	v_add_f32_e32 v44, v36, v44
	v_add_f32_e32 v45, v37, v45
	v_add_f32_e32 v46, v38, v46
	v_add_f32_e32 v47, v39, v47
	v_fma_f32 v40, v102, v98, v40
	v_fma_f32 v41, v103, v98, v41
	v_fma_f32 v42, v105, v98, v42
	v_fma_f32 v43, v106, v98, v43
	v_fma_f32 v44, v107, v98, v44
	v_fma_f32 v45, v108, v98, v45
	v_fma_f32 v46, v109, v98, v46
	v_fma_f32 v47, v114, v98, v47
	v_cndmask_b32_e64 v32, v32, v40, s[10:11]
	v_cndmask_b32_e64 v33, v33, v41, s[10:11]
	v_cndmask_b32_e64 v34, v34, v42, s[10:11]
	v_cndmask_b32_e64 v35, v35, v43, s[10:11]
	v_cndmask_b32_e64 v36, v36, v44, s[10:11]
	v_cndmask_b32_e64 v37, v37, v45, s[10:11]
	v_cndmask_b32_e64 v38, v38, v46, s[10:11]
	v_cndmask_b32_e64 v39, v39, v47, s[10:11]
	v_cvt_pk_bf16_f32 v32, v32, v33
	v_cvt_pk_bf16_f32 v33, v34, v35
	v_cvt_pk_bf16_f32 v34, v36, v37
	v_cvt_pk_bf16_f32 v35, v38, v39
	global_store_dwordx4 v113, v[32:35], s[6:7]
	s_add_u32 s6, s6, 0x300000
	s_addc_u32 s7, s7, 0
	global_load_dwordx4 v[0:3], v110, s[4:5]
	global_load_dwordx4 v[4:7], v110, s[4:5] offset:16
	global_load_dwordx4 v[8:11], v111, s[4:5]
	global_load_dwordx4 v[12:15], v111, s[4:5] offset:16
	global_load_dword v96, v112, s[8:9]
	s_add_u32 s4, s4, 0x40000
	s_addc_u32 s5, s5, 0
	s_add_u32 s8, s8, 0x100
	s_addc_u32 s9, s9, 0
	global_load_dwordx4 v[16:19], v110, s[4:5]
	global_load_dwordx4 v[20:23], v110, s[4:5] offset:16
	global_load_dwordx4 v[24:27], v111, s[4:5]
	global_load_dwordx4 v[28:31], v111, s[4:5] offset:16
	global_load_dword v97, v112, s[8:9]
	s_add_u32 s4, s4, 0x40000
	s_addc_u32 s5, s5, 0
	s_add_u32 s8, s8, 0x100
	s_addc_u32 s9, s9, 0
	global_load_dwordx4 v[32:35], v110, s[4:5]
	global_load_dwordx4 v[36:39], v110, s[4:5] offset:16
	global_load_dwordx4 v[40:43], v111, s[4:5]
	global_load_dwordx4 v[44:47], v111, s[4:5] offset:16
	global_load_dword v98, v112, s[8:9]
	s_add_u32 s4, s4, 0x40000
	s_addc_u32 s5, s5, 0
	s_add_u32 s8, s8, 0x100
	s_addc_u32 s9, s9, 0
	s_waitcnt vmcnt(18)
	v_add_f32_e32 v56, v48, v56
	v_add_f32_e32 v57, v49, v57
	v_add_f32_e32 v58, v50, v58
	v_add_f32_e32 v59, v51, v59
	v_add_f32_e32 v60, v52, v60
	v_add_f32_e32 v61, v53, v61
	v_add_f32_e32 v62, v54, v62
	v_add_f32_e32 v63, v55, v63
	v_fma_f32 v56, v102, v99, v56
	v_fma_f32 v57, v103, v99, v57
	v_fma_f32 v58, v105, v99, v58
	v_fma_f32 v59, v106, v99, v59
	v_fma_f32 v60, v107, v99, v60
	v_fma_f32 v61, v108, v99, v61
	v_fma_f32 v62, v109, v99, v62
	v_fma_f32 v63, v114, v99, v63
	v_cndmask_b32_e64 v48, v48, v56, s[10:11]
	v_cndmask_b32_e64 v49, v49, v57, s[10:11]
	v_cndmask_b32_e64 v50, v50, v58, s[10:11]
	v_cndmask_b32_e64 v51, v51, v59, s[10:11]
	v_cndmask_b32_e64 v52, v52, v60, s[10:11]
	v_cndmask_b32_e64 v53, v53, v61, s[10:11]
	v_cndmask_b32_e64 v54, v54, v62, s[10:11]
	v_cndmask_b32_e64 v55, v55, v63, s[10:11]
	v_cvt_pk_bf16_f32 v48, v48, v49
	v_cvt_pk_bf16_f32 v49, v50, v51
	v_cvt_pk_bf16_f32 v50, v52, v53
	v_cvt_pk_bf16_f32 v51, v54, v55
	global_store_dwordx4 v113, v[48:51], s[6:7]
	s_add_u32 s6, s6, 0x300000
	s_addc_u32 s7, s7, 0
	v_add_f32_e32 v72, v64, v72
	v_add_f32_e32 v73, v65, v73
	v_add_f32_e32 v74, v66, v74
	v_add_f32_e32 v75, v67, v75
	v_add_f32_e32 v76, v68, v76
	v_add_f32_e32 v77, v69, v77
	v_add_f32_e32 v78, v70, v78
	v_add_f32_e32 v79, v71, v79
	v_fma_f32 v72, v102, v100, v72
	v_fma_f32 v73, v103, v100, v73
	v_fma_f32 v74, v105, v100, v74
	v_fma_f32 v75, v106, v100, v75
	v_fma_f32 v76, v107, v100, v76
	v_fma_f32 v77, v108, v100, v77
	v_fma_f32 v78, v109, v100, v78
	v_fma_f32 v79, v114, v100, v79
	v_cndmask_b32_e64 v64, v64, v72, s[10:11]
	v_cndmask_b32_e64 v65, v65, v73, s[10:11]
	v_cndmask_b32_e64 v66, v66, v74, s[10:11]
	v_cndmask_b32_e64 v67, v67, v75, s[10:11]
	v_cndmask_b32_e64 v68, v68, v76, s[10:11]
	v_cndmask_b32_e64 v69, v69, v77, s[10:11]
	v_cndmask_b32_e64 v70, v70, v78, s[10:11]
	v_cndmask_b32_e64 v71, v71, v79, s[10:11]
	v_cvt_pk_bf16_f32 v64, v64, v65
	v_cvt_pk_bf16_f32 v65, v66, v67
	v_cvt_pk_bf16_f32 v66, v68, v69
	v_cvt_pk_bf16_f32 v67, v70, v71
	global_store_dwordx4 v113, v[64:67], s[6:7]
	s_add_u32 s6, s6, 0x300000
	s_addc_u32 s7, s7, 0
	v_add_f32_e32 v88, v80, v88
	v_add_f32_e32 v89, v81, v89
	v_add_f32_e32 v90, v82, v90
	v_add_f32_e32 v91, v83, v91
	v_add_f32_e32 v92, v84, v92
	v_add_f32_e32 v93, v85, v93
	v_add_f32_e32 v94, v86, v94
	v_add_f32_e32 v95, v87, v95
	v_fma_f32 v88, v102, v101, v88
	v_fma_f32 v89, v103, v101, v89
	v_fma_f32 v90, v105, v101, v90
	v_fma_f32 v91, v106, v101, v91
	v_fma_f32 v92, v107, v101, v92
	v_fma_f32 v93, v108, v101, v93
	v_fma_f32 v94, v109, v101, v94
	v_fma_f32 v95, v114, v101, v95
	v_cndmask_b32_e64 v80, v80, v88, s[10:11]
	v_cndmask_b32_e64 v81, v81, v89, s[10:11]
	v_cndmask_b32_e64 v82, v82, v90, s[10:11]
	v_cndmask_b32_e64 v83, v83, v91, s[10:11]
	v_cndmask_b32_e64 v84, v84, v92, s[10:11]
	v_cndmask_b32_e64 v85, v85, v93, s[10:11]
	v_cndmask_b32_e64 v86, v86, v94, s[10:11]
	v_cndmask_b32_e64 v87, v87, v95, s[10:11]
	v_cvt_pk_bf16_f32 v80, v80, v81
	v_cvt_pk_bf16_f32 v81, v82, v83
	v_cvt_pk_bf16_f32 v82, v84, v85
	v_cvt_pk_bf16_f32 v83, v86, v87
	global_store_dwordx4 v113, v[80:83], s[6:7]
	s_add_u32 s6, s6, 0x300000
	s_addc_u32 s7, s7, 0
	global_load_dwordx4 v[48:51], v110, s[4:5]
	global_load_dwordx4 v[52:55], v110, s[4:5] offset:16
	global_load_dwordx4 v[56:59], v111, s[4:5]
	global_load_dwordx4 v[60:63], v111, s[4:5] offset:16
	global_load_dword v99, v112, s[8:9]
	s_add_u32 s4, s4, 0x40000
	s_addc_u32 s5, s5, 0
	s_add_u32 s8, s8, 0x100
	s_addc_u32 s9, s9, 0
	global_load_dwordx4 v[64:67], v110, s[4:5]
	global_load_dwordx4 v[68:71], v110, s[4:5] offset:16
	global_load_dwordx4 v[72:75], v111, s[4:5]
	global_load_dwordx4 v[76:79], v111, s[4:5] offset:16
	global_load_dword v100, v112, s[8:9]
	s_add_u32 s4, s4, 0x40000
	s_addc_u32 s5, s5, 0
	s_add_u32 s8, s8, 0x100
	s_addc_u32 s9, s9, 0
	global_load_dwordx4 v[80:83], v110, s[4:5]
	global_load_dwordx4 v[84:87], v110, s[4:5] offset:16
	global_load_dwordx4 v[88:91], v111, s[4:5]
	global_load_dwordx4 v[92:95], v111, s[4:5] offset:16
	global_load_dword v101, v112, s[8:9]
	s_add_u32 s4, s4, 0x40000
	s_addc_u32 s5, s5, 0
	s_add_u32 s8, s8, 0x100
	s_addc_u32 s9, s9, 0
	s_waitcnt vmcnt(18)
; __device__ __forceinline__ unsigned pk2(float lo, float hi) { const f32x2_h v = {lo, hi}; return __builtin_bit_cast(unsigned, __builtin_convertvector(v, bf16x2_h)); }
; __global__ void __launch_bounds__(512, 2) fwd_megakernel(Params p) {
;     ...
;         for (int i = gt; i < NG * 512 * 64; i += NGT) {
;             const int c8 = i & 1, j = (i >> 1) & 31, c = (i >> 6) & 15, ii = (i >> 10) & 31, g = i >> 15;
;             float v[8];
;             if (j < ii) { const float* s = KT + (((size_t)(g * 2 + 0) * TCH + (ii - j)) * 16 + c) * 16 + 8 * c8;
; #pragma unroll
;                 for (int e = 0; e < 8; ++e) v[e] = s[e]; }
;             else if (j > ii) { const float* s = KT + (((size_t)(g * 2 + 1) * TCH + (j - ii)) * 16 + c) * 16 + 8 * c8;
; #pragma unroll
;                 for (int e = 0; e < 8; ++e) v[e] = s[e]; }
;             else { const float* s0 = KT + (((size_t)(g * 2 + 0) * TCH) * 16 + c) * 16 + 8 * c8; const float* s1 = KT + (((size_t)(g * 2 + 1) * TCH) * 16 + c) * 16 + 8 * c8;
; #pragma unroll
;                 for (int e = 0; e < 8; ++e) v[e] = s0[e] + s1[e] + ((8 * c8 + e) == c ? ssm_d[g * 16 + c] : 0.f); }
;             u32x4 o; o.x = pk2(v[0], v[1]); o.y = pk2(v[2], v[3]); o.z = pk2(v[4], v[5]); o.w = pk2(v[6], v[7]);
;             *(u32x4*)(KW + ((size_t)g * 512 + ii * 16 + c) * 768 + j * 16 + 8 * c8) = o;
;         }
	v_add_f32_e32 v8, v0, v8
	v_add_f32_e32 v9, v1, v9
	v_add_f32_e32 v10, v2, v10
	v_add_f32_e32 v11, v3, v11
	v_add_f32_e32 v12, v4, v12
	v_add_f32_e32 v13, v5, v13
	v_add_f32_e32 v14, v6, v14
	v_add_f32_e32 v15, v7, v15
	v_fma_f32 v8, v102, v96, v8
	v_fma_f32 v9, v103, v96, v9
	v_fma_f32 v10, v105, v96, v10
	v_fma_f32 v11, v106, v96, v11
	v_fma_f32 v12, v107, v96, v12
	v_fma_f32 v13, v108, v96, v13
	v_fma_f32 v14, v109, v96, v14
	v_fma_f32 v15, v114, v96, v15
	v_cndmask_b32_e64 v0, v0, v8, s[10:11]
	v_cndmask_b32_e64 v1, v1, v9, s[10:11]
	v_cndmask_b32_e64 v2, v2, v10, s[10:11]
	v_cndmask_b32_e64 v3, v3, v11, s[10:11]
	v_cndmask_b32_e64 v4, v4, v12, s[10:11]
	v_cndmask_b32_e64 v5, v5, v13, s[10:11]
	v_cndmask_b32_e64 v6, v6, v14, s[10:11]
	v_cndmask_b32_e64 v7, v7, v15, s[10:11]
	v_cvt_pk_bf16_f32 v0, v0, v1
	v_cvt_pk_bf16_f32 v1, v2, v3
	v_cvt_pk_bf16_f32 v2, v4, v5
	v_cvt_pk_bf16_f32 v3, v6, v7
	global_store_dwordx4 v113, v[0:3], s[6:7]
	s_add_u32 s6, s6, 0x300000
	s_addc_u32 s7, s7, 0
	v_add_f32_e32 v24, v16, v24
	v_add_f32_e32 v25, v17, v25
	v_add_f32_e32 v26, v18, v26
	v_add_f32_e32 v27, v19, v27
	v_add_f32_e32 v28, v20, v28
	v_add_f32_e32 v29, v21, v29
	v_add_f32_e32 v30, v22, v30
	v_add_f32_e32 v31, v23, v31
	v_fma_f32 v24, v102, v97, v24
	v_fma_f32 v25, v103, v97, v25
	v_fma_f32 v26, v105, v97, v26
	v_fma_f32 v27, v106, v97, v27
	v_fma_f32 v28, v107, v97, v28
	v_fma_f32 v29, v108, v97, v29
	v_fma_f32 v30, v109, v97, v30
	v_fma_f32 v31, v114, v97, v31
	v_cndmask_b32_e64 v16, v16, v24, s[10:11]
	v_cndmask_b32_e64 v17, v17, v25, s[10:11]
	v_cndmask_b32_e64 v18, v18, v26, s[10:11]
	v_cndmask_b32_e64 v19, v19, v27, s[10:11]
	v_cndmask_b32_e64 v20, v20, v28, s[10:11]
	v_cndmask_b32_e64 v21, v21, v29, s[10:11]
	v_cndmask_b32_e64 v22, v22, v30, s[10:11]
	v_cndmask_b32_e64 v23, v23, v31, s[10:11]
	v_cvt_pk_bf16_f32 v16, v16, v17
	v_cvt_pk_bf16_f32 v17, v18, v19
	v_cvt_pk_bf16_f32 v18, v20, v21
	v_cvt_pk_bf16_f32 v19, v22, v23
	global_store_dwordx4 v113, v[16:19], s[6:7]
	s_add_u32 s6, s6, 0x300000
	s_addc_u32 s7, s7, 0
	v_add_f32_e32 v40, v32, v40
	v_add_f32_e32 v41, v33, v41
	v_add_f32_e32 v42, v34, v42
	v_add_f32_e32 v43, v35, v43
	v_add_f32_e32 v44, v36, v44
	v_add_f32_e32 v45, v37, v45
	v_add_f32_e32 v46, v38, v46
	v_add_f32_e32 v47, v39, v47
	v_fma_f32 v40, v102, v98, v40
	v_fma_f32 v41, v103, v98, v41
	v_fma_f32 v42, v105, v98, v42
	v_fma_f32 v43, v106, v98, v43
	v_fma_f32 v44, v107, v98, v44
	v_fma_f32 v45, v108, v98, v45
	v_fma_f32 v46, v109, v98, v46
	v_fma_f32 v47, v114, v98, v47
	v_cndmask_b32_e64 v32, v32, v40, s[10:11]
	v_cndmask_b32_e64 v33, v33, v41, s[10:11]
	v_cndmask_b32_e64 v34, v34, v42, s[10:11]
	v_cndmask_b32_e64 v35, v35, v43, s[10:11]
	v_cndmask_b32_e64 v36, v36, v44, s[10:11]
	v_cndmask_b32_e64 v37, v37, v45, s[10:11]
	v_cndmask_b32_e64 v38, v38, v46, s[10:11]
	v_cndmask_b32_e64 v39, v39, v47, s[10:11]
	v_cvt_pk_bf16_f32 v32, v32, v33
	v_cvt_pk_bf16_f32 v33, v34, v35
	v_cvt_pk_bf16_f32 v34, v36, v37
	v_cvt_pk_bf16_f32 v35, v38, v39
	global_store_dwordx4 v113, v[32:35], s[6:7]
	s_add_u32 s6, s6, 0x300000
	s_addc_u32 s7, s7, 0
	global_load_dwordx4 v[0:3], v110, s[4:5]
	global_load_dwordx4 v[4:7], v110, s[4:5] offset:16
	global_load_dwordx4 v[8:11], v111, s[4:5]
	global_load_dwordx4 v[12:15], v111, s[4:5] offset:16
	global_load_dword v96, v112, s[8:9]
	s_add_u32 s4, s4, 0x40000
	s_addc_u32 s5, s5, 0
	s_add_u32 s8, s8, 0x100
	s_addc_u32 s9, s9, 0
	global_load_dwordx4 v[16:19], v110, s[4:5]
	global_load_dwordx4 v[20:23], v110, s[4:5] offset:16
	global_load_dwordx4 v[24:27], v111, s[4:5]
	global_load_dwordx4 v[28:31], v111, s[4:5] offset:16
	global_load_dword v97, v112, s[8:9]
	s_add_u32 s4, s4, 0x40000
	s_addc_u32 s5, s5, 0
	s_add_u32 s8, s8, 0x100
	s_addc_u32 s9, s9, 0
	global_load_dwordx4 v[32:35], v110, s[4:5]
	global_load_dwordx4 v[36:39], v110, s[4:5] offset:16
	global_load_dwordx4 v[40:43], v111, s[4:5]
	global_load_dwordx4 v[44:47], v111, s[4:5] offset:16
	global_load_dword v98, v112, s[8:9]
	s_add_u32 s4, s4, 0x40000
	s_addc_u32 s5, s5, 0
	s_add_u32 s8, s8, 0x100
	s_addc_u32 s9, s9, 0
	s_waitcnt vmcnt(18)
	v_add_f32_e32 v56, v48, v56
	v_add_f32_e32 v57, v49, v57
	v_add_f32_e32 v58, v50, v58
	v_add_f32_e32 v59, v51, v59
	v_add_f32_e32 v60, v52, v60
	v_add_f32_e32 v61, v53, v61
	v_add_f32_e32 v62, v54, v62
	v_add_f32_e32 v63, v55, v63
	v_fma_f32 v56, v102, v99, v56
	v_fma_f32 v57, v103, v99, v57
	v_fma_f32 v58, v105, v99, v58
	v_fma_f32 v59, v106, v99, v59
	v_fma_f32 v60, v107, v99, v60
	v_fma_f32 v61, v108, v99, v61
	v_fma_f32 v62, v109, v99, v62
	v_fma_f32 v63, v114, v99, v63
	v_cndmask_b32_e64 v48, v48, v56, s[10:11]
	v_cndmask_b32_e64 v49, v49, v57, s[10:11]
	v_cndmask_b32_e64 v50, v50, v58, s[10:11]
	v_cndmask_b32_e64 v51, v51, v59, s[10:11]
	v_cndmask_b32_e64 v52, v52, v60, s[10:11]
	v_cndmask_b32_e64 v53, v53, v61, s[10:11]
	v_cndmask_b32_e64 v54, v54, v62, s[10:11]
	v_cndmask_b32_e64 v55, v55, v63, s[10:11]
	v_cvt_pk_bf16_f32 v48, v48, v49
	v_cvt_pk_bf16_f32 v49, v50, v51
	v_cvt_pk_bf16_f32 v50, v52, v53
	v_cvt_pk_bf16_f32 v51, v54, v55
	global_store_dwordx4 v113, v[48:51], s[6:7]
	s_add_u32 s6, s6, 0x300000
	s_addc_u32 s7, s7, 0
	v_add_f32_e32 v72, v64, v72
	v_add_f32_e32 v73, v65, v73
	v_add_f32_e32 v74, v66, v74
	v_add_f32_e32 v75, v67, v75
	v_add_f32_e32 v76, v68, v76
	v_add_f32_e32 v77, v69, v77
	v_add_f32_e32 v78, v70, v78
	v_add_f32_e32 v79, v71, v79
	v_fma_f32 v72, v102, v100, v72
	v_fma_f32 v73, v103, v100, v73
	v_fma_f32 v74, v105, v100, v74
	v_fma_f32 v75, v106, v100, v75
	v_fma_f32 v76, v107, v100, v76
	v_fma_f32 v77, v108, v100, v77
	v_fma_f32 v78, v109, v100, v78
	v_fma_f32 v79, v114, v100, v79
; __device__ __forceinline__ unsigned pk2(float lo, float hi) { const f32x2_h v = {lo, hi}; return __builtin_bit_cast(unsigned, __builtin_convertvector(v, bf16x2_h)); }
; __global__ void __launch_bounds__(512, 2) fwd_megakernel(Params p) {
;     ...
;         for (int i = gt; i < NG * 512 * 64; i += NGT) {
;             const int c8 = i & 1, j = (i >> 1) & 31, c = (i >> 6) & 15, ii = (i >> 10) & 31, g = i >> 15;
;             float v[8];
;             if (j < ii) { const float* s = KT + (((size_t)(g * 2 + 0) * TCH + (ii - j)) * 16 + c) * 16 + 8 * c8;
; #pragma unroll
;                 for (int e = 0; e < 8; ++e) v[e] = s[e]; }
;             else if (j > ii) { const float* s = KT + (((size_t)(g * 2 + 1) * TCH + (j - ii)) * 16 + c) * 16 + 8 * c8;
; #pragma unroll
;                 for (int e = 0; e < 8; ++e) v[e] = s[e]; }
;             else { const float* s0 = KT + (((size_t)(g * 2 + 0) * TCH) * 16 + c) * 16 + 8 * c8; const float* s1 = KT + (((size_t)(g * 2 + 1) * TCH) * 16 + c) * 16 + 8 * c8;
; #pragma unroll
;                 for (int e = 0; e < 8; ++e) v[e] = s0[e] + s1[e] + ((8 * c8 + e) == c ? ssm_d[g * 16 + c] : 0.f); }
;             u32x4 o; o.x = pk2(v[0], v[1]); o.y = pk2(v[2], v[3]); o.z = pk2(v[4], v[5]); o.w = pk2(v[6], v[7]);
;             *(u32x4*)(KW + ((size_t)g * 512 + ii * 16 + c) * 768 + j * 16 + 8 * c8) = o;
;         }
	v_cndmask_b32_e64 v64, v64, v72, s[10:11]
	v_cndmask_b32_e64 v65, v65, v73, s[10:11]
	v_cndmask_b32_e64 v66, v66, v74, s[10:11]
	v_cndmask_b32_e64 v67, v67, v75, s[10:11]
	v_cndmask_b32_e64 v68, v68, v76, s[10:11]
	v_cndmask_b32_e64 v69, v69, v77, s[10:11]
	v_cndmask_b32_e64 v70, v70, v78, s[10:11]
	v_cndmask_b32_e64 v71, v71, v79, s[10:11]
	v_cvt_pk_bf16_f32 v64, v64, v65
	v_cvt_pk_bf16_f32 v65, v66, v67
	v_cvt_pk_bf16_f32 v66, v68, v69
	v_cvt_pk_bf16_f32 v67, v70, v71
	global_store_dwordx4 v113, v[64:67], s[6:7]
	s_add_u32 s6, s6, 0x300000
	s_addc_u32 s7, s7, 0
	v_add_f32_e32 v88, v80, v88
	v_add_f32_e32 v89, v81, v89
	v_add_f32_e32 v90, v82, v90
	v_add_f32_e32 v91, v83, v91
	v_add_f32_e32 v92, v84, v92
	v_add_f32_e32 v93, v85, v93
	v_add_f32_e32 v94, v86, v94
	v_add_f32_e32 v95, v87, v95
	v_fma_f32 v88, v102, v101, v88
	v_fma_f32 v89, v103, v101, v89
	v_fma_f32 v90, v105, v101, v90
	v_fma_f32 v91, v106, v101, v91
	v_fma_f32 v92, v107, v101, v92
	v_fma_f32 v93, v108, v101, v93
	v_fma_f32 v94, v109, v101, v94
	v_fma_f32 v95, v114, v101, v95
	v_cndmask_b32_e64 v80, v80, v88, s[10:11]
	v_cndmask_b32_e64 v81, v81, v89, s[10:11]
	v_cndmask_b32_e64 v82, v82, v90, s[10:11]
	v_cndmask_b32_e64 v83, v83, v91, s[10:11]
	v_cndmask_b32_e64 v84, v84, v92, s[10:11]
	v_cndmask_b32_e64 v85, v85, v93, s[10:11]
	v_cndmask_b32_e64 v86, v86, v94, s[10:11]
	v_cndmask_b32_e64 v87, v87, v95, s[10:11]
	v_cvt_pk_bf16_f32 v80, v80, v81
	v_cvt_pk_bf16_f32 v81, v82, v83
	v_cvt_pk_bf16_f32 v82, v84, v85
	v_cvt_pk_bf16_f32 v83, v86, v87
	global_store_dwordx4 v113, v[80:83], s[6:7]
	s_add_u32 s6, s6, 0x300000
	s_addc_u32 s7, s7, 0
	global_load_dwordx4 v[48:51], v110, s[4:5]
	global_load_dwordx4 v[52:55], v110, s[4:5] offset:16
	global_load_dwordx4 v[56:59], v111, s[4:5]
	global_load_dwordx4 v[60:63], v111, s[4:5] offset:16
	global_load_dword v99, v112, s[8:9]
	s_add_u32 s4, s4, 0x40000
	s_addc_u32 s5, s5, 0
	s_add_u32 s8, s8, 0x100
	s_addc_u32 s9, s9, 0
	s_waitcnt vmcnt(8)
	v_add_f32_e32 v8, v0, v8
	v_add_f32_e32 v9, v1, v9
	v_add_f32_e32 v10, v2, v10
	v_add_f32_e32 v11, v3, v11
	v_add_f32_e32 v12, v4, v12
	v_add_f32_e32 v13, v5, v13
	v_add_f32_e32 v14, v6, v14
	v_add_f32_e32 v15, v7, v15
	v_fma_f32 v8, v102, v96, v8
	v_fma_f32 v9, v103, v96, v9
	v_fma_f32 v10, v105, v96, v10
	v_fma_f32 v11, v106, v96, v11
	v_fma_f32 v12, v107, v96, v12
	v_fma_f32 v13, v108, v96, v13
	v_fma_f32 v14, v109, v96, v14
	v_fma_f32 v15, v114, v96, v15
	v_cndmask_b32_e64 v0, v0, v8, s[10:11]
	v_cndmask_b32_e64 v1, v1, v9, s[10:11]
	v_cndmask_b32_e64 v2, v2, v10, s[10:11]
	v_cndmask_b32_e64 v3, v3, v11, s[10:11]
	v_cndmask_b32_e64 v4, v4, v12, s[10:11]
	v_cndmask_b32_e64 v5, v5, v13, s[10:11]
	v_cndmask_b32_e64 v6, v6, v14, s[10:11]
	v_cndmask_b32_e64 v7, v7, v15, s[10:11]
	v_cvt_pk_bf16_f32 v0, v0, v1
	v_cvt_pk_bf16_f32 v1, v2, v3
	v_cvt_pk_bf16_f32 v2, v4, v5
	v_cvt_pk_bf16_f32 v3, v6, v7
	global_store_dwordx4 v113, v[0:3], s[6:7]
	s_add_u32 s6, s6, 0x300000
	s_addc_u32 s7, s7, 0
	v_add_f32_e32 v24, v16, v24
	v_add_f32_e32 v25, v17, v25
	v_add_f32_e32 v26, v18, v26
	v_add_f32_e32 v27, v19, v27
	v_add_f32_e32 v28, v20, v28
	v_add_f32_e32 v29, v21, v29
	v_add_f32_e32 v30, v22, v30
	v_add_f32_e32 v31, v23, v31
	v_fma_f32 v24, v102, v97, v24
	v_fma_f32 v25, v103, v97, v25
	v_fma_f32 v26, v105, v97, v26
	v_fma_f32 v27, v106, v97, v27
	v_fma_f32 v28, v107, v97, v28
	v_fma_f32 v29, v108, v97, v29
	v_fma_f32 v30, v109, v97, v30
	v_fma_f32 v31, v114, v97, v31
	v_cndmask_b32_e64 v16, v16, v24, s[10:11]
	v_cndmask_b32_e64 v17, v17, v25, s[10:11]
	v_cndmask_b32_e64 v18, v18, v26, s[10:11]
	v_cndmask_b32_e64 v19, v19, v27, s[10:11]
	v_cndmask_b32_e64 v20, v20, v28, s[10:11]
	v_cndmask_b32_e64 v21, v21, v29, s[10:11]
	v_cndmask_b32_e64 v22, v22, v30, s[10:11]
	v_cndmask_b32_e64 v23, v23, v31, s[10:11]
	v_cvt_pk_bf16_f32 v16, v16, v17
	v_cvt_pk_bf16_f32 v17, v18, v19
	v_cvt_pk_bf16_f32 v18, v20, v21
	v_cvt_pk_bf16_f32 v19, v22, v23
	global_store_dwordx4 v113, v[16:19], s[6:7]
	s_add_u32 s6, s6, 0x300000
	s_addc_u32 s7, s7, 0
	v_add_f32_e32 v40, v32, v40
	v_add_f32_e32 v41, v33, v41
	v_add_f32_e32 v42, v34, v42
	v_add_f32_e32 v43, v35, v43
	v_add_f32_e32 v44, v36, v44
	v_add_f32_e32 v45, v37, v45
	v_add_f32_e32 v46, v38, v46
	v_add_f32_e32 v47, v39, v47
	v_fma_f32 v40, v102, v98, v40
	v_fma_f32 v41, v103, v98, v41
	v_fma_f32 v42, v105, v98, v42
	v_fma_f32 v43, v106, v98, v43
	v_fma_f32 v44, v107, v98, v44
	v_fma_f32 v45, v108, v98, v45
	v_fma_f32 v46, v109, v98, v46
	v_fma_f32 v47, v114, v98, v47
	v_cndmask_b32_e64 v32, v32, v40, s[10:11]
	v_cndmask_b32_e64 v33, v33, v41, s[10:11]
	v_cndmask_b32_e64 v34, v34, v42, s[10:11]
	v_cndmask_b32_e64 v35, v35, v43, s[10:11]
	v_cndmask_b32_e64 v36, v36, v44, s[10:11]
	v_cndmask_b32_e64 v37, v37, v45, s[10:11]
	v_cndmask_b32_e64 v38, v38, v46, s[10:11]
	v_cndmask_b32_e64 v39, v39, v47, s[10:11]
	v_cvt_pk_bf16_f32 v32, v32, v33
	v_cvt_pk_bf16_f32 v33, v34, v35
	v_cvt_pk_bf16_f32 v34, v36, v37
	v_cvt_pk_bf16_f32 v35, v38, v39
	global_store_dwordx4 v113, v[32:35], s[6:7]
	s_add_u32 s6, s6, 0x300000
	s_addc_u32 s7, s7, 0
	s_waitcnt vmcnt(3)
	v_add_f32_e32 v56, v48, v56
	v_add_f32_e32 v57, v49, v57
	v_add_f32_e32 v58, v50, v58
	v_add_f32_e32 v59, v51, v59
	v_add_f32_e32 v60, v52, v60
	v_add_f32_e32 v61, v53, v61
	v_add_f32_e32 v62, v54, v62
	v_add_f32_e32 v63, v55, v63
	v_fma_f32 v56, v102, v99, v56
	v_fma_f32 v57, v103, v99, v57
	v_fma_f32 v58, v105, v99, v58
	v_fma_f32 v59, v106, v99, v59
	v_fma_f32 v60, v107, v99, v60
	v_fma_f32 v61, v108, v99, v61
	v_fma_f32 v62, v109, v99, v62
	v_fma_f32 v63, v114, v99, v63
	v_cndmask_b32_e64 v48, v48, v56, s[10:11]
	v_cndmask_b32_e64 v49, v49, v57, s[10:11]
	v_cndmask_b32_e64 v50, v50, v58, s[10:11]
	v_cndmask_b32_e64 v51, v51, v59, s[10:11]
	v_cndmask_b32_e64 v52, v52, v60, s[10:11]
	v_cndmask_b32_e64 v53, v53, v61, s[10:11]
	v_cndmask_b32_e64 v54, v54, v62, s[10:11]
	v_cndmask_b32_e64 v55, v55, v63, s[10:11]
	v_cvt_pk_bf16_f32 v48, v48, v49
	v_cvt_pk_bf16_f32 v49, v50, v51
	v_cvt_pk_bf16_f32 v50, v52, v53
	v_cvt_pk_bf16_f32 v51, v54, v55
	global_store_dwordx4 v113, v[48:51], s[6:7]
	s_add_u32 s6, s6, 0x300000
	s_addc_u32 s7, s7, 0
